# attention steady loop: dead per-lane pointer advances and the two x+0 adds removed (4 VALU fewer per step)
# baseline (speedup 1.0000x reference)
.LBB0_77:
	v_add_u32_e32 v0, s44, v233
	ds_read_b64_tr_b16 v[62:63], v0 offset:24576
	ds_read_b64_tr_b16 v[64:65], v0 offset:25088
	v_add_f32_e32 v51, v82, v83
	v_add_f32_e32 v51, v84, v51
	v_add_f32_e32 v51, v85, v51
	v_add_f32_e32 v51, v86, v51
	v_add_f32_e32 v51, v87, v51
	v_cvt_pk_f16_f32 v160, v82, v83
	v_cvt_pk_f16_f32 v161, v84, v85
	s_waitcnt lgkmcnt(9)
	v_mfma_f32_32x32x16_f16 v[114:129], v[192:195], v[144:147], v[2:17]
	ds_read_b64_tr_b16 v[82:83], v0 offset:28672
	ds_read_b64_tr_b16 v[84:85], v0 offset:29184
	v_add_f32_e32 v51, v88, v51
	v_add_f32_e32 v51, v89, v51
	v_add_f32_e32 v51, v90, v51
	v_add_f32_e32 v51, v91, v51
	v_cvt_pk_f16_f32 v162, v86, v87
	v_cvt_pk_f16_f32 v163, v88, v89
	s_waitcnt lgkmcnt(10)
	v_mfma_f32_32x32x16_f16 v[98:113], v[188:191], v[144:147], v[2:17]
	ds_read_b64_tr_b16 v[86:87], v0 offset:25600
	ds_read_b64_tr_b16 v[88:89], v0 offset:26112
	v_add_f32_e32 v51, v92, v51
	v_add_f32_e32 v51, v93, v51
	v_add_f32_e32 v51, v94, v51
	v_add_f32_e32 v51, v95, v51
	v_cvt_pk_f16_f32 v156, v90, v91
	v_cvt_pk_f16_f32 v157, v92, v93
	s_waitcnt lgkmcnt(11)
	v_mfma_f32_32x32x16_f16 v[114:129], v[184:187], v[140:143], v[114:129]
	ds_read_b64_tr_b16 v[90:91], v0 offset:29696
	ds_read_b64_tr_b16 v[92:93], v0 offset:30208
	v_add_f32_e32 v51, v96, v51
	v_add_f32_e32 v51, v97, v51
	v_add_f32_e32 v51, v66, v51
	v_add_f32_e32 v51, v67, v51
	v_cvt_pk_f16_f32 v158, v94, v95
	v_cvt_pk_f16_f32 v159, v96, v97
	s_waitcnt lgkmcnt(12)
	v_mfma_f32_32x32x16_f16 v[98:113], v[180:183], v[140:143], v[98:113]
	ds_read_b64_tr_b16 v[94:95], v0 offset:26624
	ds_read_b64_tr_b16 v[96:97], v0 offset:27136
	v_add_f32_e32 v51, v68, v51
	v_add_f32_e32 v51, v69, v51
	v_add_f32_e32 v51, v70, v51
	v_add_f32_e32 v51, v71, v51
	v_cvt_pk_f16_f32 v152, v66, v67
	v_cvt_pk_f16_f32 v153, v68, v69
	s_waitcnt lgkmcnt(13)
	v_mfma_f32_32x32x16_f16 v[114:129], v[176:179], v[136:139], v[114:129]
	ds_read_b64_tr_b16 v[66:67], v0 offset:30720
	ds_read_b64_tr_b16 v[68:69], v0 offset:31232
	v_add_f32_e32 v51, v72, v51
	v_add_f32_e32 v51, v73, v51
	v_add_f32_e32 v51, v74, v51
	v_add_f32_e32 v51, v75, v51
	v_cvt_pk_f16_f32 v154, v70, v71
	v_cvt_pk_f16_f32 v155, v72, v73
	s_waitcnt lgkmcnt(14)
	v_mfma_f32_32x32x16_f16 v[98:113], v[172:175], v[136:139], v[98:113]
	ds_read_b64_tr_b16 v[70:71], v0 offset:27648
	ds_read_b64_tr_b16 v[72:73], v0 offset:28160
	v_add_f32_e32 v51, v76, v51
	v_add_f32_e32 v51, v77, v51
	v_add_f32_e32 v51, v78, v51
	v_add_f32_e32 v51, v79, v51
	v_cvt_pk_f16_f32 v148, v74, v75
	v_cvt_pk_f16_f32 v149, v76, v77
	s_waitcnt lgkmcnt(14)
	v_mfma_f32_32x32x16_f16 v[114:129], v[168:171], v[132:135], v[114:129]
	ds_read_b64_tr_b16 v[74:75], v0 offset:31744
	ds_read_b64_tr_b16 v[76:77], v0 offset:32256
	v_add_f32_e32 v0, v80, v51
	v_add_f32_e32 v0, v81, v0
	v_cvt_pk_f16_f32 v150, v78, v79
	v_cvt_pk_f16_f32 v151, v80, v81
	v_mfma_f32_32x32x16_f16 v[98:113], v[164:167], v[132:135], v[98:113]
	v_add_f32_e32 v0, v50, v0
	s_add_i32 s43, s42, s97
	s_mov_b32 s44, m0
	s_mov_b32 m0, s43
	s_nop 0
	global_load_lds_dwordx4 v214, s[100:101]
	s_mov_b32 m0, s44
	s_add_i32 s43, s25, s83
	s_mov_b32 s44, m0
	s_mov_b32 m0, s43
	s_nop 0
	global_load_lds_dwordx4 v208, vcc
	s_mov_b32 m0, s44
	s_add_u32 s100, s100, 0x2000
	s_addc_u32 s101, s101, 0
	s_add_u32 vcc_lo, vcc_lo, 0x2000
	s_addc_u32 vcc_hi, vcc_hi, 0
	s_waitcnt lgkmcnt(14)
	v_mfma_f32_32x32x16_f16 v[18:33], v[160:163], v[62:65], v[18:33]
	v_exp_f32_e32 v114, v114
	v_exp_f32_e32 v115, v115
	v_exp_f32_e32 v116, v116
	v_exp_f32_e32 v117, v117
	s_waitcnt lgkmcnt(12)
	v_mfma_f32_32x32x16_f16 v[34:49], v[160:163], v[82:85], v[34:49]
	v_exp_f32_e32 v118, v118
	v_exp_f32_e32 v119, v119
	v_exp_f32_e32 v120, v120
	v_exp_f32_e32 v121, v121
	v_add_u32_e32 v50, s25, v219
	ds_read_b128 v[62:65], v50
	ds_read_b128 v[164:167], v50 offset:512
	s_waitcnt lgkmcnt(12)
	v_mfma_f32_32x32x16_f16 v[18:33], v[156:159], v[86:89], v[18:33]
	v_exp_f32_e32 v122, v122
	v_exp_f32_e32 v123, v123
	v_exp_f32_e32 v124, v124
	v_exp_f32_e32 v125, v125
	ds_read_b128 v[168:171], v50 offset:2048
	ds_read_b128 v[172:175], v50 offset:2560
	s_waitcnt lgkmcnt(12)
	v_mfma_f32_32x32x16_f16 v[34:49], v[156:159], v[90:93], v[34:49]
	v_exp_f32_e32 v126, v126
	v_exp_f32_e32 v127, v127
	v_exp_f32_e32 v128, v128
	v_exp_f32_e32 v129, v129
	ds_read_b128 v[176:179], v50 offset:4096
	ds_read_b128 v[180:183], v50 offset:4608
	s_waitcnt lgkmcnt(12)
	v_mfma_f32_32x32x16_f16 v[18:33], v[152:155], v[94:97], v[18:33]
	v_exp_f32_e32 v98, v98
	v_exp_f32_e32 v99, v99
	v_exp_f32_e32 v100, v100
	v_exp_f32_e32 v101, v101
	ds_read_b128 v[184:187], v50 offset:6144
	ds_read_b128 v[50:53], v50 offset:6656
	s_waitcnt lgkmcnt(12)
	v_mfma_f32_32x32x16_f16 v[34:49], v[152:155], v[66:69], v[34:49]
	v_exp_f32_e32 v102, v102
	v_exp_f32_e32 v103, v103
	v_exp_f32_e32 v104, v104
	v_exp_f32_e32 v105, v105
	s_waitcnt lgkmcnt(10)
	v_mfma_f32_32x32x16_f16 v[18:33], v[148:151], v[70:73], v[18:33]
	v_exp_f32_e32 v106, v106
	v_exp_f32_e32 v107, v107
	v_exp_f32_e32 v108, v108
	v_exp_f32_e32 v109, v109
	s_waitcnt lgkmcnt(8)
	v_mfma_f32_32x32x16_f16 v[34:49], v[148:151], v[74:77], v[34:49]
	v_exp_f32_e32 v110, v110
	v_exp_f32_e32 v111, v111
	v_exp_f32_e32 v112, v112
	v_exp_f32_e32 v113, v113
	s_waitcnt vmcnt(2) lgkmcnt(8)
	s_barrier
; #define WAIT_BAR(N) asm volatile("s_waitcnt vmcnt(" #N ") lgkmcnt(0)\n\ts_barrier" ::: "memory")
; #define RESC() do { if (!FIXM && resc) { asm volatile("s_waitcnt lgkmcnt(0)" ::: "memory"); \
;       _Pragma("unroll") for (int d_ = 0; d_ < 2; ++d_) _Pragma("unroll") for (int r = 0; r < 16; ++r) o[d_][r] *= wsf[crow(r, hi)]; } } while (0)
; #define ROT() do { sl_prev = sl_cur; sl_cur = sl_next; sl_next = (sl_next == (NSLOT - 1) * SLOTB) ? 0 : sl_next + SLOTB; } while (0)
; template <int THRL, bool FIXM> __device__ __forceinline__ bool attn_unit(const h16* Qrows, const h16* __restrict__ Kh, const h16* __restrict__ Vh, const int NT, h16* Yrows, const h16* BZrows, char* shm, const int tid, const float mfix, ...
;     ...
;   int t = 1;
;   for (; t + 5 < NT; t += 2) {
;     STEP(pB0, pB1, pA0, pA1, t, true, true, true);     WAIT_BAR(2); RESC(); ROT();
;     STEP(pA0, pA1, pB0, pB1, t + 1, true, true, true); WAIT_BAR(2); RESC(); ROT();
	s_add_i32 s43, s25, 0x2000
	s_cmpk_lg_i32 s25, 0x4000
	s_cselect_b32 s43, s43, 0
	v_add_u32_e32 v192, s42, v233
	ds_read_b64_tr_b16 v[188:189], v192 offset:24576
	ds_read_b64_tr_b16 v[190:191], v192 offset:25088
	s_waitcnt lgkmcnt(9)
	v_mfma_f32_32x32x16_f16 v[82:97], v[62:65], v[144:147], v[2:17]
	v_add_f32_e32 v66, v114, v115
	v_add_f32_e32 v66, v116, v66
	v_add_f32_e32 v66, v117, v66
	v_add_f32_e32 v66, v118, v66
	v_add_f32_e32 v66, v119, v66
	v_cvt_pk_f16_f32 v160, v114, v115
	v_cvt_pk_f16_f32 v161, v116, v117
	ds_read_b64_tr_b16 v[62:63], v192 offset:28672
	ds_read_b64_tr_b16 v[64:65], v192 offset:29184
	v_add_f32_e32 v66, v120, v66
	v_add_f32_e32 v66, v121, v66
	v_add_f32_e32 v66, v122, v66
	v_add_f32_e32 v148, v123, v66
	s_waitcnt lgkmcnt(10)
	v_mfma_f32_32x32x16_f16 v[66:81], v[164:167], v[144:147], v[2:17]
	v_cvt_pk_f16_f32 v162, v118, v119
	v_cvt_pk_f16_f32 v163, v120, v121
	ds_read_b64_tr_b16 v[114:115], v192 offset:25600
	ds_read_b64_tr_b16 v[116:117], v192 offset:26112
	s_waitcnt lgkmcnt(11)
	v_mfma_f32_32x32x16_f16 v[82:97], v[168:171], v[140:143], v[82:97]
	v_add_f32_e32 v118, v124, v148
	v_add_f32_e32 v118, v125, v118
	v_add_f32_e32 v118, v126, v118
	v_add_f32_e32 v148, v127, v118
	v_cvt_pk_f16_f32 v156, v122, v123
	v_cvt_pk_f16_f32 v157, v124, v125
	ds_read_b64_tr_b16 v[118:119], v192 offset:29696
	ds_read_b64_tr_b16 v[120:121], v192 offset:30208
	s_waitcnt lgkmcnt(12)
	v_mfma_f32_32x32x16_f16 v[66:81], v[172:175], v[140:143], v[66:81]
	v_add_f32_e32 v122, v128, v148
	v_add_f32_e32 v122, v129, v122
	v_add_f32_e32 v122, v98, v122
	v_add_f32_e32 v148, v99, v122
	v_cvt_pk_f16_f32 v158, v126, v127
	v_cvt_pk_f16_f32 v159, v128, v129
	ds_read_b64_tr_b16 v[122:123], v192 offset:26624
	ds_read_b64_tr_b16 v[124:125], v192 offset:27136
	s_waitcnt lgkmcnt(13)
	v_mfma_f32_32x32x16_f16 v[82:97], v[176:179], v[136:139], v[82:97]
	v_add_f32_e32 v126, v100, v148
	v_add_f32_e32 v126, v101, v126
	v_add_f32_e32 v126, v102, v126
	v_add_f32_e32 v126, v103, v126
	v_cvt_pk_f16_f32 v152, v98, v99
	v_cvt_pk_f16_f32 v153, v100, v101
	ds_read_b64_tr_b16 v[98:99], v192 offset:30720
	ds_read_b64_tr_b16 v[100:101], v192 offset:31232
	s_waitcnt lgkmcnt(14)
	v_mfma_f32_32x32x16_f16 v[66:81], v[180:183], v[136:139], v[66:81]
	v_add_f32_e32 v126, v104, v126
	v_add_f32_e32 v126, v105, v126
	v_add_f32_e32 v126, v106, v126
	v_add_f32_e32 v126, v107, v126
	v_cvt_pk_f16_f32 v154, v102, v103
	v_cvt_pk_f16_f32 v155, v104, v105
	ds_read_b64_tr_b16 v[102:103], v192 offset:27648
	ds_read_b64_tr_b16 v[104:105], v192 offset:28160
	s_waitcnt lgkmcnt(14)
	v_mfma_f32_32x32x16_f16 v[82:97], v[184:187], v[132:135], v[82:97]
	v_add_f32_e32 v126, v108, v126
	v_add_f32_e32 v126, v109, v126
	v_add_f32_e32 v126, v110, v126
	v_add_f32_e32 v126, v111, v126
	v_cvt_pk_f16_f32 v148, v106, v107
	v_cvt_pk_f16_f32 v149, v108, v109
	ds_read_b64_tr_b16 v[106:107], v192 offset:31744
	ds_read_b64_tr_b16 v[108:109], v192 offset:32256
	v_mfma_f32_32x32x16_f16 v[66:81], v[50:53], v[132:135], v[66:81]
	v_add_f32_e32 v50, v112, v126
	v_add_f32_e32 v50, v113, v50
	v_cvt_pk_f16_f32 v150, v110, v111
	v_cvt_pk_f16_f32 v151, v112, v113
	s_add_i32 s42, s25, s97
	s_mov_b32 s44, m0
	s_mov_b32 m0, s42
	s_nop 0
	global_load_lds_dwordx4 v214, s[100:101]
	s_mov_b32 m0, s44
	s_add_i32 s42, s43, s83
	s_mov_b32 s44, m0
	s_mov_b32 m0, s42
	s_nop 0
	global_load_lds_dwordx4 v208, vcc
	s_mov_b32 m0, s44
	s_add_u32 s100, s100, 0x2000
	s_addc_u32 s101, s101, 0
	s_add_u32 vcc_lo, vcc_lo, 0x2000
	s_addc_u32 vcc_hi, vcc_hi, 0
	v_add_f32_e32 v50, v0, v50
	s_waitcnt lgkmcnt(14)
	v_mfma_f32_32x32x16_f16 v[18:33], v[160:163], v[188:191], v[18:33]
	v_exp_f32_e32 v82, v82
	v_exp_f32_e32 v83, v83
	v_exp_f32_e32 v84, v84
	v_exp_f32_e32 v85, v85
	s_waitcnt lgkmcnt(12)
	v_mfma_f32_32x32x16_f16 v[34:49], v[160:163], v[62:65], v[34:49]
	v_exp_f32_e32 v86, v86
	v_exp_f32_e32 v87, v87
	v_exp_f32_e32 v88, v88
	v_exp_f32_e32 v89, v89
	v_add_u32_e32 v0, s43, v219
	ds_read_b128 v[192:195], v0
	ds_read_b128 v[188:191], v0 offset:512
	s_waitcnt lgkmcnt(12)
	v_mfma_f32_32x32x16_f16 v[18:33], v[156:159], v[114:117], v[18:33]
	v_exp_f32_e32 v90, v90
	v_exp_f32_e32 v91, v91
	v_exp_f32_e32 v92, v92
	v_exp_f32_e32 v93, v93
	ds_read_b128 v[184:187], v0 offset:2048
	ds_read_b128 v[180:183], v0 offset:2560
	s_waitcnt lgkmcnt(12)
	v_mfma_f32_32x32x16_f16 v[34:49], v[156:159], v[118:121], v[34:49]
	v_exp_f32_e32 v94, v94
	v_exp_f32_e32 v95, v95
	v_exp_f32_e32 v96, v96
	v_exp_f32_e32 v97, v97
	ds_read_b128 v[176:179], v0 offset:4096
	ds_read_b128 v[172:175], v0 offset:4608
	s_waitcnt lgkmcnt(12)
	v_mfma_f32_32x32x16_f16 v[18:33], v[152:155], v[122:125], v[18:33]
	v_exp_f32_e32 v66, v66
	v_exp_f32_e32 v67, v67
	v_exp_f32_e32 v68, v68
	v_exp_f32_e32 v69, v69
	ds_read_b128 v[168:171], v0 offset:6144
	ds_read_b128 v[164:167], v0 offset:6656
	s_waitcnt lgkmcnt(12)
	v_mfma_f32_32x32x16_f16 v[34:49], v[152:155], v[98:101], v[34:49]
	v_exp_f32_e32 v70, v70
	v_exp_f32_e32 v71, v71
	v_exp_f32_e32 v72, v72
	v_exp_f32_e32 v73, v73
	s_waitcnt lgkmcnt(10)
	v_mfma_f32_32x32x16_f16 v[18:33], v[148:151], v[102:105], v[18:33]
	v_exp_f32_e32 v74, v74
	v_exp_f32_e32 v75, v75
	v_exp_f32_e32 v76, v76
	v_exp_f32_e32 v77, v77
	s_waitcnt lgkmcnt(8)
	v_mfma_f32_32x32x16_f16 v[34:49], v[148:151], v[106:109], v[34:49]
	v_exp_f32_e32 v78, v78
	v_exp_f32_e32 v79, v79
	v_exp_f32_e32 v80, v80
	v_exp_f32_e32 v81, v81
	s_add_i32 s45, s43, 0x2000
	s_waitcnt vmcnt(2) lgkmcnt(8)
	s_barrier
	s_cmpk_lg_i32 s43, 0x4000
	s_mov_b32 s44, s25
	s_cselect_b32 s25, s45, 0
	s_add_i32 s24, s24, 2
	s_mov_b32 s42, s43
	s_cmp_lt_u32 s24, 29
	s_cbranch_scc1 .LBB0_77
	s_mov_b64 s[36:37], 0x10c84000
	s_mov_b64 s[60:61], 0x10388000
	s_mov_b32 s45, 31
	s_branch .LBB0_80
